# scan fix + retO tasks of all two-B-task blocks moved to their one-B-task CU partners
# baseline (speedup 1.0000x reference)
.LBB0_181:
	s_or_b64 exec, exec, s[0:1]
	v_readlane_b32 s0, v242, 8
	v_readlane_b32 s1, v242, 9
	s_and_b64 vcc, exec, s[0:1]
	s_barrier
	s_cbranch_vccnz .LBB0_194
	s_cmp_lt_u32 s95, 32
	s_cbranch_scc1 .LBB0_194
	v_readlane_b32 s0, v242, 14
	v_readlane_b32 s1, v242, 15
	s_and_b64 s[0:1], s[0:1], exec
	s_cselect_b32 s0, 6, 9
	v_readlane_b32 s1, v242, 4
	s_lshl_b32 s0, s1, s0
	v_writelane_b32 v242, s0, 25
	s_nop 0
	v_readlane_b32 s0, v242, 17
	v_readlane_b32 s1, v242, 18
	s_mulk_i32 s0, 0x60
	s_ashr_i32 s1, s0, 31
	s_lshl_b64 s[0:1], s[0:1], 2
	s_branch .LBB0_184
.LBB0_183:
	v_readlane_b32 s95, v242, 24
	v_readlane_b32 s98, v242, 22
	v_readlane_b32 s99, v242, 23
	s_cmp_lt_u32 s95, 32
	s_cbranch_scc1 .LBB0_194
	s_sub_u32 s95, s95, 32
